# e37: e33 with the P2 stagger classes split by XCD parity (bit 0 of blockIdx) instead of within each XCD (bit 3): every XCD stays in lockstep for L2 operand sharing, the HBM-level stagger remains
# baseline (speedup 1.0000x reference)
; #define LAS __attribute__((address_space(3)))
; #define SUB(i, ...) do { if (PROBE_PH == phk && PROBE_SUB == (i)) { __syncthreads(); tp0 = __builtin_amdgcn_s_memrealtime(); } __VA_ARGS__ if (PROBE_PH == phk && PROBE_SUB == (i)) { asm volatile("s_waitcnt vmcnt(0)" ::: "memory"); __syncthreads(); tp1 = __builtin_amdgcn_s_memrealtime(); } } while (0)
; __global__ void __launch_bounds__(NTHREADS, 2) mk_fwd(Args a) {
;     ...
;     PHASE(2,
;         pg8::DenseOrder S; S.init(M_LAT / 256, 12, G, bx, WGM_IN);
;         EpiInProj E{(f16*)(a.ws + WS_UPOOL), (f16*)(a.ws + WS_X), (f16*)(a.ws + WS_ZS)};
;         SUB(0, pg8::gemm_phase<CfgDense2048, EpiInProj, pg8::DenseOrder, true, true>(lds, (const char*)(a.ws + WS_H), (const char*)(a.ws + WS_WIN), S, E); );
;         for (int it = bx; it < 256; it += G) ctx_item((LAS float*)lds, it, (const f16*)(a.ws + WS_H) + (size_t)M_LAT * D, (const f16*)(a.ws + WS_WIN) + (size_t)PW * D, (f16*)(a.ws + WS_X));
.LBB0_284:
	s_mov_b32 s98, 0
	s_cmp_lt_i32 s78, 3
	s_cselect_b64 s[0:1], -1, 0
	s_and_b64 s[6:7], s[0:1], s[2:3]
	s_andn2_b64 vcc, exec, s[6:7]
	s_cbranch_vccnz .LBB0_436
	s_bitcmp1_b32 s16, 0
	s_cbranch_scc0 .Lp2_gemm
	s_mov_b32 s98, 1
	v_lshrrev_b32_e32 v1, 3, v0
	v_and_b32_e32 v130, 15, v0
	v_lshrrev_b32_e32 v131, 2, v0
	s_add_u32 s8, s50, 0xc300000
	s_addc_u32 s9, s51, 0
	s_branch .LBB0_431
